# prep_qk row loop with two rows of loads in flight (two register sets, unrolled by two) instead of one
# baseline (speedup 1.0000x reference)
.LBB0_338:
	s_mov_b64 s[12:13], s[84:85]
	v_mov_b32_e32 v0, v173
	s_getreg_b32 s1, hwreg(HW_REG_HW_ID, 0, 7)
	s_and_b32 s1, s1, 63
	s_lshl_b32 s1, s1, 2
	v_mov_b32_e32 v1, s1
	ds_read_b32 v1, v1
	v_readlane_b32 s6, v254, 10
	v_readlane_b32 s7, v254, 11
	s_andn2_b64 vcc, exec, s[6:7]
	s_waitcnt lgkmcnt(0)
	v_readfirstlane_b32 s1, v1
	s_lshl_b32 s1, s1, 6
	s_and_b32 s1, s1, 0x3fc0
	v_cndmask_b32_e64 v2, 0, 1, s[6:7]
	v_add_u32_e32 v1, s1, v0
	v_cmp_ne_u32_e64 s[10:11], 1, v2
	v_readfirstlane_b32 s1, v1
	s_cbranch_vccnz .LBB0_342
	s_ashr_i32 s1, s1, 6
	v_readlane_b32 s6, v254, 12
	s_add_i32 s14, s6, s1
	s_cmpk_gt_i32 s14, 0x3fff
	s_cbranch_scc1 .LBB0_342
	s_load_dwordx4 s[16:19], s[12:13], 0x80
	v_and_b32_e32 v1, 63, v0
	v_cmp_lt_u32_e32 vcc, 31, v1
	s_lshl_b32 s40, s70, 6
	s_ashr_i32 s15, s14, 31
	s_waitcnt lgkmcnt(0)
	v_mov_b32_e32 v1, s17
	v_mov_b32_e32 v2, s19
	v_cndmask_b32_e32 v3, v1, v2, vcc
	v_mov_b32_e32 v1, s16
	v_mov_b32_e32 v2, s18
	v_cndmask_b32_e32 v2, v1, v2, vcc
	v_mov_b32_e32 v1, 0x3e38aa3b
	v_cndmask_b32_e64 v14, v1, 1.0, vcc
	v_lshlrev_b32_e32 v1, 5, v0
	v_lshl_add_u64 v[2:3], s[40:41], 2, v[2:3]
	v_and_b32_e32 v160, 0x60, v1
	v_lshl_add_u64 v[16:17], v[2:3], 0, v[160:161]
	global_load_dwordx4 v[2:5], v[16:17], off offset:16
	global_load_dwordx4 v[6:9], v[16:17], off
	global_load_dwordx4 v[10:13], v[16:17], off offset:144
	global_load_dwordx4 v[20:23], v[16:17], off offset:128
	s_load_dwordx2 s[16:17], s[12:13], 0xe0
	s_lshl_b64 s[6:7], s[14:15], 8
	v_and_b32_e32 v0, 3, v0
	v_and_b32_e32 v160, 0x780, v1
	s_waitcnt vmcnt(16)
	v_lshl_or_b32 v32, v0, 6, s6
	v_mov_b32_e32 v33, s7
	v_mad_i64_i32 v[34:35], s[6:7], s14, v194, v[160:161]
	v_lshl_or_b32 v34, v0, 4, v34
	s_waitcnt vmcnt(3)
	v_pk_mul_f32 v[24:25], v[14:15], v[2:3] op_sel_hi:[0,1]
	s_waitcnt vmcnt(2)
	v_pk_mul_f32 v[16:17], v[14:15], v[6:7] op_sel_hi:[0,1]
	s_waitcnt vmcnt(1)
	v_pk_mul_f32 v[26:27], v[14:15], v[10:11] op_sel_hi:[0,1]
	s_waitcnt vmcnt(0)
	v_pk_mul_f32 v[18:19], v[14:15], v[20:21] op_sel_hi:[0,1]
	v_pk_mul_f32 v[20:21], v[14:15], v[8:9] op_sel_hi:[0,1]
	v_pk_mul_f32 v[22:23], v[14:15], v[22:23] op_sel_hi:[0,1]
	v_pk_mul_f32 v[28:29], v[14:15], v[4:5] op_sel_hi:[0,1]
	v_pk_mul_f32 v[30:31], v[14:15], v[12:13] op_sel_hi:[0,1]
	s_waitcnt lgkmcnt(0)
	v_lshl_add_u64 v[102:103], s[16:17], 0, v[34:35]
	v_add_co_u32_e32 v100, vcc, 0xc000000, v102
	s_mov_b64 s[6:7], 0xf600000
	s_nop 0
	v_addc_co_u32_e32 v101, vcc, 0, v103, vcc
	global_load_dwordx4 v[108:111], v[100:101], off
	global_load_dwordx4 v[112:115], v[100:101], off offset:64
	v_lshl_add_u64 v[102:103], s[16:17], 0, v[32:33]
	s_mov_b32 s1, 0xf600000
	v_lshl_add_u64 v[104:105], v[102:103], 0, s[6:7]
	v_add_co_u32_e32 v102, vcc, s1, v102
	s_add_i32 s14, s14, s38
	s_nop 0
	v_addc_co_u32_e32 v103, vcc, 0, v103, vcc
	global_load_dwordx4 v[116:119], v[102:103], off
	s_nop 0
	global_load_dwordx4 v[120:123], v[104:105], off offset:48
	global_load_dwordx4 v[124:127], v[104:105], off offset:32
	s_nop 0
	global_load_dwordx4 v[128:131], v[104:105], off offset:16
	v_lshl_add_u64 v[32:33], v[32:33], 0, s[66:67]
	v_lshl_add_u64 v[34:35], v[34:35], 0, s[62:63]
	s_cmpk_lt_i32 s14, 0x4000
	s_cselect_b32 s15, 1, 0
	v_lshl_add_u64 v[98:99], s[16:17], 0, v[34:35]
	v_add_co_u32_e32 v96, vcc, 0xc000000, v98
	s_mov_b64 s[6:7], 0xf600000
	s_nop 0
	v_addc_co_u32_e32 v97, vcc, 0, v99, vcc
	global_load_dwordx4 v[132:135], v[96:97], off
	global_load_dwordx4 v[136:139], v[96:97], off offset:64
	v_lshl_add_u64 v[98:99], s[16:17], 0, v[32:33]
	s_mov_b32 s1, 0xf600000
	v_lshl_add_u64 v[156:157], v[98:99], 0, s[6:7]
	v_add_co_u32_e32 v98, vcc, s1, v98
	s_add_i32 s14, s14, s38
	s_nop 0
	v_addc_co_u32_e32 v99, vcc, 0, v99, vcc
	global_load_dwordx4 v[140:143], v[98:99], off
	s_nop 0
	global_load_dwordx4 v[144:147], v[156:157], off offset:48
	global_load_dwordx4 v[148:151], v[156:157], off offset:32
	s_nop 0
	global_load_dwordx4 v[152:155], v[156:157], off offset:16
	v_lshl_add_u64 v[32:33], v[32:33], 0, s[66:67]
	v_lshl_add_u64 v[34:35], v[34:35], 0, s[62:63]
	s_cmpk_lt_i32 s14, 0x4000
	s_cselect_b32 s42, 1, 0
	s_waitcnt vmcnt(6)
	v_mov_b32_e32 v46, v108
	v_mov_b32_e32 v47, v109
	v_mov_b32_e32 v48, v110
	v_mov_b32_e32 v49, v111
	v_mov_b32_e32 v50, v112
	v_mov_b32_e32 v51, v113
	v_mov_b32_e32 v52, v114
	v_mov_b32_e32 v53, v115
	v_mov_b32_e32 v12, v116
	v_mov_b32_e32 v13, v117
	v_mov_b32_e32 v14, v118
	v_mov_b32_e32 v15, v119
	v_mov_b32_e32 v0, v120
	v_mov_b32_e32 v1, v121
	v_mov_b32_e32 v2, v122
	v_mov_b32_e32 v3, v123
	v_mov_b32_e32 v4, v124
	v_mov_b32_e32 v5, v125
	v_mov_b32_e32 v6, v126
	v_mov_b32_e32 v7, v127
	v_mov_b32_e32 v8, v128
	v_mov_b32_e32 v9, v129
	v_mov_b32_e32 v10, v130
	v_mov_b32_e32 v11, v131
	v_mov_b32_e32 v36, v100
	v_mov_b32_e32 v37, v101
	v_lshl_add_u64 v[102:103], s[16:17], 0, v[34:35]
	v_add_co_u32_e32 v100, vcc, 0xc000000, v102
	s_mov_b64 s[6:7], 0xf600000
	s_nop 0
	v_addc_co_u32_e32 v101, vcc, 0, v103, vcc
	global_load_dwordx4 v[108:111], v[100:101], off
	global_load_dwordx4 v[112:115], v[100:101], off offset:64
	v_lshl_add_u64 v[102:103], s[16:17], 0, v[32:33]
	s_mov_b32 s1, 0xf600000
	v_lshl_add_u64 v[104:105], v[102:103], 0, s[6:7]
	v_add_co_u32_e32 v102, vcc, s1, v102
	s_add_i32 s14, s14, s38
	s_nop 0
	v_addc_co_u32_e32 v103, vcc, 0, v103, vcc
	global_load_dwordx4 v[116:119], v[102:103], off
	s_nop 0
	global_load_dwordx4 v[120:123], v[104:105], off offset:48
	global_load_dwordx4 v[124:127], v[104:105], off offset:32
	s_nop 0
	global_load_dwordx4 v[128:131], v[104:105], off offset:16
	v_lshl_add_u64 v[32:33], v[32:33], 0, s[66:67]
	v_lshl_add_u64 v[34:35], v[34:35], 0, s[62:63]
	v_lshlrev_b32_e32 v40, 16, v49
	v_lshlrev_b32_e32 v38, 16, v53
	v_and_b32_e32 v39, 0xffff0000, v53
	v_and_b32_e32 v41, 0xffff0000, v49
	v_pk_mul_f32 v[42:43], v[38:39], v[38:39]
	v_and_b32_e32 v53, 0xffff0000, v47
	v_pk_fma_f32 v[54:55], v[40:41], v[40:41], v[42:43]
	v_lshlrev_b32_e32 v42, 16, v52
	v_and_b32_e32 v43, 0xffff0000, v52
	v_lshlrev_b32_e32 v52, 16, v47
	v_lshlrev_b32_e32 v60, 16, v46
	v_and_b32_e32 v61, 0xffff0000, v46
	v_lshlrev_b32_e32 v46, 16, v50
	v_and_b32_e32 v47, 0xffff0000, v50
	v_lshlrev_b32_e32 v56, 16, v51
	v_and_b32_e32 v57, 0xffff0000, v51
	v_pk_mul_f32 v[50:51], v[46:47], v[46:47]
	v_pk_mul_f32 v[58:59], v[56:57], v[56:57]
	v_pk_fma_f32 v[50:51], v[60:61], v[60:61], v[50:51]
	v_pk_fma_f32 v[58:59], v[52:53], v[52:53], v[58:59]
	v_add_f32_e32 v50, v50, v51
	v_lshlrev_b32_e32 v44, 16, v48
	v_and_b32_e32 v45, 0xffff0000, v48
	v_pk_mul_f32 v[48:49], v[42:43], v[42:43]
	v_add_f32_e32 v50, v58, v50
	v_pk_fma_f32 v[48:49], v[44:45], v[44:45], v[48:49]
	v_add_f32_e32 v50, v59, v50
	v_add_f32_e32 v48, v48, v50
	v_add_f32_e32 v48, v49, v48
	v_add_f32_e32 v48, v54, v48
	v_add_f32_e32 v48, v55, v48
	s_nop 1
	v_add_f32_dpp v48, v48, v48 quad_perm:[1,0,3,2] row_mask:0xf bank_mask:0xf bound_ctrl:1
	s_nop 1
	v_add_f32_dpp v48, v48, v48 quad_perm:[2,3,0,1] row_mask:0xf bank_mask:0xf bound_ctrl:1
	v_fmamk_f32 v48, v48, 0x3c800000, v182
	v_cmp_gt_f32_e32 vcc, s50, v48
	v_mul_f32_e32 v49, 0x4f800000, v48
	s_nop 0
	v_cndmask_b32_e32 v48, v48, v49, vcc
	v_sqrt_f32_e32 v49, v48
	s_nop 0
	v_add_u32_e32 v50, -1, v49
	v_fma_f32 v51, -v50, v49, v48
	v_cmp_ge_f32_e64 s[12:13], 0, v51
	v_add_u32_e32 v51, 1, v49
	s_nop 0
	v_cndmask_b32_e64 v50, v49, v50, s[12:13]
	v_fma_f32 v49, -v51, v49, v48
	v_cmp_lt_f32_e64 s[12:13], 0, v49
	s_nop 1
	v_cndmask_b32_e64 v49, v50, v51, s[12:13]
	v_mul_f32_e32 v50, 0x37800000, v49
	v_cndmask_b32_e32 v49, v49, v50, vcc
	v_cmp_class_f32_e32 vcc, v48, v183
	s_nop 1
	v_cndmask_b32_e32 v48, v49, v48, vcc
	v_div_scale_f32 v49, s[6:7], v48, v48, 1.0
	v_rcp_f32_e32 v50, v49
	s_nop 0
	v_fma_f32 v51, -v49, v50, 1.0
	v_fmac_f32_e32 v50, v51, v50
	v_div_scale_f32 v51, vcc, 1.0, v48, 1.0
	v_mul_f32_e32 v54, v51, v50
	v_fma_f32 v55, -v49, v54, v51
	v_fmac_f32_e32 v54, v55, v50
	v_fma_f32 v49, -v49, v54, v51
	v_div_fmas_f32 v49, v49, v50, v54
	v_div_fixup_f32 v50, v49, v48, 1.0
	v_pk_mul_f32 v[46:47], v[50:51], v[46:47] op_sel_hi:[0,1]
	v_pk_mul_f32 v[48:49], v[50:51], v[60:61] op_sel_hi:[0,1]
	v_pk_mul_f32 v[46:47], v[18:19], v[46:47]
	v_mov_b32_e32 v54, v12
	v_mov_b32_e32 v55, v14
	v_mov_b32_e32 v14, v13
	v_pk_mul_f32 v[48:49], v[16:17], v[48:49]
	v_pk_mul_f32 v[12:13], v[14:15], v[46:47]
	v_pk_mul_f32 v[46:47], v[54:55], v[46:47]
	v_pk_fma_f32 v[12:13], v[54:55], v[48:49], v[12:13] neg_lo:[0,0,1] neg_hi:[0,0,1]
	v_pk_fma_f32 v[14:15], v[14:15], v[48:49], v[46:47]
	v_pk_mul_f32 v[48:49], v[50:51], v[56:57] op_sel_hi:[0,1]
	v_cvt_pk_bf16_f32 v46, v14, v15
	v_pk_mul_f32 v[14:15], v[50:51], v[52:53] op_sel_hi:[0,1]
	v_pk_mul_f32 v[48:49], v[22:23], v[48:49]
	v_mov_b32_e32 v53, v10
	v_mov_b32_e32 v10, v9
	v_pk_mul_f32 v[14:15], v[20:21], v[14:15]
	v_mov_b32_e32 v52, v8
	v_pk_mul_f32 v[8:9], v[10:11], v[48:49]
	v_cvt_pk_bf16_f32 v12, v12, v13
	v_pk_fma_f32 v[8:9], v[52:53], v[14:15], v[8:9] neg_lo:[0,0,1] neg_hi:[0,0,1]
	s_nop 0
	v_cvt_pk_bf16_f32 v13, v8, v9
	v_pk_mul_f32 v[8:9], v[52:53], v[48:49]
	s_nop 0
	v_pk_fma_f32 v[8:9], v[10:11], v[14:15], v[8:9]
	v_pk_mul_f32 v[10:11], v[50:51], v[42:43] op_sel_hi:[0,1]
	v_cvt_pk_bf16_f32 v47, v8, v9
	v_pk_mul_f32 v[8:9], v[50:51], v[44:45] op_sel_hi:[0,1]
	v_pk_mul_f32 v[10:11], v[26:27], v[10:11]
	v_mov_b32_e32 v43, v6
	v_mov_b32_e32 v6, v5
	v_pk_mul_f32 v[8:9], v[24:25], v[8:9]
	v_mov_b32_e32 v42, v4
	v_pk_mul_f32 v[4:5], v[6:7], v[10:11]
	s_nop 0
	v_pk_fma_f32 v[4:5], v[42:43], v[8:9], v[4:5] neg_lo:[0,0,1] neg_hi:[0,0,1]
	s_nop 0
	v_cvt_pk_bf16_f32 v14, v4, v5
	v_pk_mul_f32 v[4:5], v[42:43], v[10:11]
	s_nop 0
	v_pk_fma_f32 v[4:5], v[6:7], v[8:9], v[4:5]
	v_pk_mul_f32 v[6:7], v[50:51], v[38:39] op_sel_hi:[0,1]
	v_cvt_pk_bf16_f32 v48, v4, v5
	v_pk_mul_f32 v[4:5], v[50:51], v[40:41] op_sel_hi:[0,1]
	v_pk_mul_f32 v[6:7], v[30:31], v[6:7]
	v_mov_b32_e32 v9, v2
	v_mov_b32_e32 v2, v1
	v_pk_mul_f32 v[4:5], v[28:29], v[4:5]
	v_mov_b32_e32 v8, v0
	v_pk_mul_f32 v[0:1], v[2:3], v[6:7]
	s_nop 0
	v_pk_fma_f32 v[0:1], v[8:9], v[4:5], v[0:1] neg_lo:[0,0,1] neg_hi:[0,0,1]
	s_nop 0
	v_cvt_pk_bf16_f32 v15, v0, v1
	v_pk_mul_f32 v[0:1], v[8:9], v[6:7]
	s_nop 0
	v_pk_fma_f32 v[0:1], v[2:3], v[4:5], v[0:1]
	s_nop 0
	v_cvt_pk_bf16_f32 v49, v0, v1
	global_store_dwordx4 v[36:37], v[12:15], off
	global_store_dwordx4 v[36:37], v[46:49], off offset:64
	s_cmp_lg_u32 s15, 0
	s_cbranch_scc0 .Lpq_exit
	s_cmpk_lt_i32 s14, 0x4000
	s_cselect_b32 s15, 1, 0
	s_waitcnt vmcnt(8)
	v_mov_b32_e32 v46, v132
	v_mov_b32_e32 v47, v133
	v_mov_b32_e32 v48, v134
	v_mov_b32_e32 v49, v135
	v_mov_b32_e32 v50, v136
	v_mov_b32_e32 v51, v137
	v_mov_b32_e32 v52, v138
	v_mov_b32_e32 v53, v139
	v_mov_b32_e32 v12, v140
	v_mov_b32_e32 v13, v141
	v_mov_b32_e32 v14, v142
	v_mov_b32_e32 v15, v143
	v_mov_b32_e32 v0, v144
	v_mov_b32_e32 v1, v145
	v_mov_b32_e32 v2, v146
	v_mov_b32_e32 v3, v147
	v_mov_b32_e32 v4, v148
	v_mov_b32_e32 v5, v149
	v_mov_b32_e32 v6, v150
	v_mov_b32_e32 v7, v151
	v_mov_b32_e32 v8, v152
	v_mov_b32_e32 v9, v153
	v_mov_b32_e32 v10, v154
	v_mov_b32_e32 v11, v155
	v_mov_b32_e32 v36, v96
	v_mov_b32_e32 v37, v97
	v_lshl_add_u64 v[98:99], s[16:17], 0, v[34:35]
	v_add_co_u32_e32 v96, vcc, 0xc000000, v98
	s_mov_b64 s[6:7], 0xf600000
	s_nop 0
	v_addc_co_u32_e32 v97, vcc, 0, v99, vcc
	global_load_dwordx4 v[132:135], v[96:97], off
	global_load_dwordx4 v[136:139], v[96:97], off offset:64
	v_lshl_add_u64 v[98:99], s[16:17], 0, v[32:33]
	s_mov_b32 s1, 0xf600000
	v_lshl_add_u64 v[156:157], v[98:99], 0, s[6:7]
	v_add_co_u32_e32 v98, vcc, s1, v98
	s_add_i32 s14, s14, s38
	s_nop 0
	v_addc_co_u32_e32 v99, vcc, 0, v99, vcc
	global_load_dwordx4 v[140:143], v[98:99], off
	s_nop 0
	global_load_dwordx4 v[144:147], v[156:157], off offset:48
	global_load_dwordx4 v[148:151], v[156:157], off offset:32
	s_nop 0
	global_load_dwordx4 v[152:155], v[156:157], off offset:16
	v_lshl_add_u64 v[32:33], v[32:33], 0, s[66:67]
	v_lshl_add_u64 v[34:35], v[34:35], 0, s[62:63]
	v_lshlrev_b32_e32 v40, 16, v49
	v_lshlrev_b32_e32 v38, 16, v53
	v_and_b32_e32 v39, 0xffff0000, v53
	v_and_b32_e32 v41, 0xffff0000, v49
	v_pk_mul_f32 v[42:43], v[38:39], v[38:39]
	v_and_b32_e32 v53, 0xffff0000, v47
	v_pk_fma_f32 v[54:55], v[40:41], v[40:41], v[42:43]
	v_lshlrev_b32_e32 v42, 16, v52
	v_and_b32_e32 v43, 0xffff0000, v52
	v_lshlrev_b32_e32 v52, 16, v47
	v_lshlrev_b32_e32 v60, 16, v46
	v_and_b32_e32 v61, 0xffff0000, v46
	v_lshlrev_b32_e32 v46, 16, v50
	v_and_b32_e32 v47, 0xffff0000, v50
	v_lshlrev_b32_e32 v56, 16, v51
	v_and_b32_e32 v57, 0xffff0000, v51
	v_pk_mul_f32 v[50:51], v[46:47], v[46:47]
	v_pk_mul_f32 v[58:59], v[56:57], v[56:57]
	v_pk_fma_f32 v[50:51], v[60:61], v[60:61], v[50:51]
	v_pk_fma_f32 v[58:59], v[52:53], v[52:53], v[58:59]
	v_add_f32_e32 v50, v50, v51
	v_lshlrev_b32_e32 v44, 16, v48
	v_and_b32_e32 v45, 0xffff0000, v48
	v_pk_mul_f32 v[48:49], v[42:43], v[42:43]
	v_add_f32_e32 v50, v58, v50
	v_pk_fma_f32 v[48:49], v[44:45], v[44:45], v[48:49]
	v_add_f32_e32 v50, v59, v50
	v_add_f32_e32 v48, v48, v50
	v_add_f32_e32 v48, v49, v48
	v_add_f32_e32 v48, v54, v48
	v_add_f32_e32 v48, v55, v48
	s_nop 1
	v_add_f32_dpp v48, v48, v48 quad_perm:[1,0,3,2] row_mask:0xf bank_mask:0xf bound_ctrl:1
	s_nop 1
	v_add_f32_dpp v48, v48, v48 quad_perm:[2,3,0,1] row_mask:0xf bank_mask:0xf bound_ctrl:1
	v_fmamk_f32 v48, v48, 0x3c800000, v182
	v_cmp_gt_f32_e32 vcc, s50, v48
	v_mul_f32_e32 v49, 0x4f800000, v48
	s_nop 0
	v_cndmask_b32_e32 v48, v48, v49, vcc
	v_sqrt_f32_e32 v49, v48
	s_nop 0
	v_add_u32_e32 v50, -1, v49
	v_fma_f32 v51, -v50, v49, v48
	v_cmp_ge_f32_e64 s[12:13], 0, v51
	v_add_u32_e32 v51, 1, v49
	s_nop 0
	v_cndmask_b32_e64 v50, v49, v50, s[12:13]
	v_fma_f32 v49, -v51, v49, v48
	v_cmp_lt_f32_e64 s[12:13], 0, v49
	s_nop 1
	v_cndmask_b32_e64 v49, v50, v51, s[12:13]
	v_mul_f32_e32 v50, 0x37800000, v49
	v_cndmask_b32_e32 v49, v49, v50, vcc
	v_cmp_class_f32_e32 vcc, v48, v183
	s_nop 1
	v_cndmask_b32_e32 v48, v49, v48, vcc
	v_div_scale_f32 v49, s[6:7], v48, v48, 1.0
	v_rcp_f32_e32 v50, v49
	s_nop 0
	v_fma_f32 v51, -v49, v50, 1.0
	v_fmac_f32_e32 v50, v51, v50
	v_div_scale_f32 v51, vcc, 1.0, v48, 1.0
	v_mul_f32_e32 v54, v51, v50
	v_fma_f32 v55, -v49, v54, v51
	v_fmac_f32_e32 v54, v55, v50
	v_fma_f32 v49, -v49, v54, v51
	v_div_fmas_f32 v49, v49, v50, v54
	v_div_fixup_f32 v50, v49, v48, 1.0
	v_pk_mul_f32 v[46:47], v[50:51], v[46:47] op_sel_hi:[0,1]
	v_pk_mul_f32 v[48:49], v[50:51], v[60:61] op_sel_hi:[0,1]
	v_pk_mul_f32 v[46:47], v[18:19], v[46:47]
	v_mov_b32_e32 v54, v12
	v_mov_b32_e32 v55, v14
	v_mov_b32_e32 v14, v13
	v_pk_mul_f32 v[48:49], v[16:17], v[48:49]
	v_pk_mul_f32 v[12:13], v[14:15], v[46:47]
	v_pk_mul_f32 v[46:47], v[54:55], v[46:47]
	v_pk_fma_f32 v[12:13], v[54:55], v[48:49], v[12:13] neg_lo:[0,0,1] neg_hi:[0,0,1]
	v_pk_fma_f32 v[14:15], v[14:15], v[48:49], v[46:47]
	v_pk_mul_f32 v[48:49], v[50:51], v[56:57] op_sel_hi:[0,1]
	v_cvt_pk_bf16_f32 v46, v14, v15
	v_pk_mul_f32 v[14:15], v[50:51], v[52:53] op_sel_hi:[0,1]
	v_pk_mul_f32 v[48:49], v[22:23], v[48:49]
	v_mov_b32_e32 v53, v10
	v_mov_b32_e32 v10, v9
	v_pk_mul_f32 v[14:15], v[20:21], v[14:15]
	v_mov_b32_e32 v52, v8
	v_pk_mul_f32 v[8:9], v[10:11], v[48:49]
	v_cvt_pk_bf16_f32 v12, v12, v13
	v_pk_fma_f32 v[8:9], v[52:53], v[14:15], v[8:9] neg_lo:[0,0,1] neg_hi:[0,0,1]
	s_nop 0
	v_cvt_pk_bf16_f32 v13, v8, v9
	v_pk_mul_f32 v[8:9], v[52:53], v[48:49]
	s_nop 0
	v_pk_fma_f32 v[8:9], v[10:11], v[14:15], v[8:9]
	v_pk_mul_f32 v[10:11], v[50:51], v[42:43] op_sel_hi:[0,1]
	v_cvt_pk_bf16_f32 v47, v8, v9
	v_pk_mul_f32 v[8:9], v[50:51], v[44:45] op_sel_hi:[0,1]
	v_pk_mul_f32 v[10:11], v[26:27], v[10:11]
	v_mov_b32_e32 v43, v6
	v_mov_b32_e32 v6, v5
	v_pk_mul_f32 v[8:9], v[24:25], v[8:9]
	v_mov_b32_e32 v42, v4
	v_pk_mul_f32 v[4:5], v[6:7], v[10:11]
	s_nop 0
	v_pk_fma_f32 v[4:5], v[42:43], v[8:9], v[4:5] neg_lo:[0,0,1] neg_hi:[0,0,1]
	s_nop 0
	v_cvt_pk_bf16_f32 v14, v4, v5
	v_pk_mul_f32 v[4:5], v[42:43], v[10:11]
	s_nop 0
	v_pk_fma_f32 v[4:5], v[6:7], v[8:9], v[4:5]
	v_pk_mul_f32 v[6:7], v[50:51], v[38:39] op_sel_hi:[0,1]
	v_cvt_pk_bf16_f32 v48, v4, v5
	v_pk_mul_f32 v[4:5], v[50:51], v[40:41] op_sel_hi:[0,1]
	v_pk_mul_f32 v[6:7], v[30:31], v[6:7]
	v_mov_b32_e32 v9, v2
	v_mov_b32_e32 v2, v1
	v_pk_mul_f32 v[4:5], v[28:29], v[4:5]
	v_mov_b32_e32 v8, v0
	v_pk_mul_f32 v[0:1], v[2:3], v[6:7]
	s_nop 0
	v_pk_fma_f32 v[0:1], v[8:9], v[4:5], v[0:1] neg_lo:[0,0,1] neg_hi:[0,0,1]
	s_nop 0
	v_cvt_pk_bf16_f32 v15, v0, v1
	v_pk_mul_f32 v[0:1], v[8:9], v[6:7]
	s_nop 0
	v_pk_fma_f32 v[0:1], v[2:3], v[4:5], v[0:1]
	s_nop 0
	v_cvt_pk_bf16_f32 v49, v0, v1
	global_store_dwordx4 v[36:37], v[12:15], off
	global_store_dwordx4 v[36:37], v[46:49], off offset:64
	s_cmp_lg_u32 s42, 0
	s_cbranch_scc0 .Lpq_exit
.LBB0_341:
	s_cmpk_lt_i32 s14, 0x4000
	s_cselect_b32 s42, 1, 0
	s_waitcnt vmcnt(10)
	v_mov_b32_e32 v46, v108
	v_mov_b32_e32 v47, v109
	v_mov_b32_e32 v48, v110
	v_mov_b32_e32 v49, v111
	v_mov_b32_e32 v50, v112
	v_mov_b32_e32 v51, v113
	v_mov_b32_e32 v52, v114
	v_mov_b32_e32 v53, v115
	v_mov_b32_e32 v12, v116
	v_mov_b32_e32 v13, v117
	v_mov_b32_e32 v14, v118
	v_mov_b32_e32 v15, v119
	v_mov_b32_e32 v0, v120
	v_mov_b32_e32 v1, v121
	v_mov_b32_e32 v2, v122
	v_mov_b32_e32 v3, v123
	v_mov_b32_e32 v4, v124
	v_mov_b32_e32 v5, v125
	v_mov_b32_e32 v6, v126
	v_mov_b32_e32 v7, v127
	v_mov_b32_e32 v8, v128
	v_mov_b32_e32 v9, v129
	v_mov_b32_e32 v10, v130
	v_mov_b32_e32 v11, v131
	v_mov_b32_e32 v36, v100
	v_mov_b32_e32 v37, v101
	v_lshl_add_u64 v[102:103], s[16:17], 0, v[34:35]
	v_add_co_u32_e32 v100, vcc, 0xc000000, v102
	s_mov_b64 s[6:7], 0xf600000
	s_nop 0
	v_addc_co_u32_e32 v101, vcc, 0, v103, vcc
	global_load_dwordx4 v[108:111], v[100:101], off
	global_load_dwordx4 v[112:115], v[100:101], off offset:64
	v_lshl_add_u64 v[102:103], s[16:17], 0, v[32:33]
	s_mov_b32 s1, 0xf600000
	v_lshl_add_u64 v[104:105], v[102:103], 0, s[6:7]
	v_add_co_u32_e32 v102, vcc, s1, v102
	s_add_i32 s14, s14, s38
	s_nop 0
	v_addc_co_u32_e32 v103, vcc, 0, v103, vcc
	global_load_dwordx4 v[116:119], v[102:103], off
	s_nop 0
	global_load_dwordx4 v[120:123], v[104:105], off offset:48
	global_load_dwordx4 v[124:127], v[104:105], off offset:32
	s_nop 0
	global_load_dwordx4 v[128:131], v[104:105], off offset:16
	v_lshl_add_u64 v[32:33], v[32:33], 0, s[66:67]
	v_lshl_add_u64 v[34:35], v[34:35], 0, s[62:63]
	v_lshlrev_b32_e32 v40, 16, v49
	v_lshlrev_b32_e32 v38, 16, v53
	v_and_b32_e32 v39, 0xffff0000, v53
	v_and_b32_e32 v41, 0xffff0000, v49
	v_pk_mul_f32 v[42:43], v[38:39], v[38:39]
	v_and_b32_e32 v53, 0xffff0000, v47
	v_pk_fma_f32 v[54:55], v[40:41], v[40:41], v[42:43]
	v_lshlrev_b32_e32 v42, 16, v52
	v_and_b32_e32 v43, 0xffff0000, v52
	v_lshlrev_b32_e32 v52, 16, v47
	v_lshlrev_b32_e32 v60, 16, v46
	v_and_b32_e32 v61, 0xffff0000, v46
	v_lshlrev_b32_e32 v46, 16, v50
	v_and_b32_e32 v47, 0xffff0000, v50
	v_lshlrev_b32_e32 v56, 16, v51
	v_and_b32_e32 v57, 0xffff0000, v51
	v_pk_mul_f32 v[50:51], v[46:47], v[46:47]
	v_pk_mul_f32 v[58:59], v[56:57], v[56:57]
	v_pk_fma_f32 v[50:51], v[60:61], v[60:61], v[50:51]
	v_pk_fma_f32 v[58:59], v[52:53], v[52:53], v[58:59]
	v_add_f32_e32 v50, v50, v51
	v_lshlrev_b32_e32 v44, 16, v48
	v_and_b32_e32 v45, 0xffff0000, v48
	v_pk_mul_f32 v[48:49], v[42:43], v[42:43]
	v_add_f32_e32 v50, v58, v50
	v_pk_fma_f32 v[48:49], v[44:45], v[44:45], v[48:49]
	v_add_f32_e32 v50, v59, v50
	v_add_f32_e32 v48, v48, v50
	v_add_f32_e32 v48, v49, v48
	v_add_f32_e32 v48, v54, v48
	v_add_f32_e32 v48, v55, v48
	s_nop 1
	v_add_f32_dpp v48, v48, v48 quad_perm:[1,0,3,2] row_mask:0xf bank_mask:0xf bound_ctrl:1
	s_nop 1
	v_add_f32_dpp v48, v48, v48 quad_perm:[2,3,0,1] row_mask:0xf bank_mask:0xf bound_ctrl:1
	v_fmamk_f32 v48, v48, 0x3c800000, v182
	v_cmp_gt_f32_e32 vcc, s50, v48
	v_mul_f32_e32 v49, 0x4f800000, v48
	s_nop 0
	v_cndmask_b32_e32 v48, v48, v49, vcc
	v_sqrt_f32_e32 v49, v48
	s_nop 0
	v_add_u32_e32 v50, -1, v49
	v_fma_f32 v51, -v50, v49, v48
	v_cmp_ge_f32_e64 s[12:13], 0, v51
	v_add_u32_e32 v51, 1, v49
	s_nop 0
	v_cndmask_b32_e64 v50, v49, v50, s[12:13]
	v_fma_f32 v49, -v51, v49, v48
	v_cmp_lt_f32_e64 s[12:13], 0, v49
	s_nop 1
	v_cndmask_b32_e64 v49, v50, v51, s[12:13]
	v_mul_f32_e32 v50, 0x37800000, v49
	v_cndmask_b32_e32 v49, v49, v50, vcc
	v_cmp_class_f32_e32 vcc, v48, v183
	s_nop 1
	v_cndmask_b32_e32 v48, v49, v48, vcc
	v_div_scale_f32 v49, s[6:7], v48, v48, 1.0
	v_rcp_f32_e32 v50, v49
	s_nop 0
	v_fma_f32 v51, -v49, v50, 1.0
	v_fmac_f32_e32 v50, v51, v50
	v_div_scale_f32 v51, vcc, 1.0, v48, 1.0
	v_mul_f32_e32 v54, v51, v50
	v_fma_f32 v55, -v49, v54, v51
	v_fmac_f32_e32 v54, v55, v50
	v_fma_f32 v49, -v49, v54, v51
	v_div_fmas_f32 v49, v49, v50, v54
	v_div_fixup_f32 v50, v49, v48, 1.0
	v_pk_mul_f32 v[46:47], v[50:51], v[46:47] op_sel_hi:[0,1]
	v_pk_mul_f32 v[48:49], v[50:51], v[60:61] op_sel_hi:[0,1]
	v_pk_mul_f32 v[46:47], v[18:19], v[46:47]
	v_mov_b32_e32 v54, v12
	v_mov_b32_e32 v55, v14
	v_mov_b32_e32 v14, v13
	v_pk_mul_f32 v[48:49], v[16:17], v[48:49]
	v_pk_mul_f32 v[12:13], v[14:15], v[46:47]
	v_pk_mul_f32 v[46:47], v[54:55], v[46:47]
	v_pk_fma_f32 v[12:13], v[54:55], v[48:49], v[12:13] neg_lo:[0,0,1] neg_hi:[0,0,1]
	v_pk_fma_f32 v[14:15], v[14:15], v[48:49], v[46:47]
	v_pk_mul_f32 v[48:49], v[50:51], v[56:57] op_sel_hi:[0,1]
	v_cvt_pk_bf16_f32 v46, v14, v15
	v_pk_mul_f32 v[14:15], v[50:51], v[52:53] op_sel_hi:[0,1]
	v_pk_mul_f32 v[48:49], v[22:23], v[48:49]
	v_mov_b32_e32 v53, v10
	v_mov_b32_e32 v10, v9
	v_pk_mul_f32 v[14:15], v[20:21], v[14:15]
	v_mov_b32_e32 v52, v8
	v_pk_mul_f32 v[8:9], v[10:11], v[48:49]
	v_cvt_pk_bf16_f32 v12, v12, v13
	v_pk_fma_f32 v[8:9], v[52:53], v[14:15], v[8:9] neg_lo:[0,0,1] neg_hi:[0,0,1]
	s_nop 0
	v_cvt_pk_bf16_f32 v13, v8, v9
	v_pk_mul_f32 v[8:9], v[52:53], v[48:49]
	s_nop 0
	v_pk_fma_f32 v[8:9], v[10:11], v[14:15], v[8:9]
	v_pk_mul_f32 v[10:11], v[50:51], v[42:43] op_sel_hi:[0,1]
	v_cvt_pk_bf16_f32 v47, v8, v9
	v_pk_mul_f32 v[8:9], v[50:51], v[44:45] op_sel_hi:[0,1]
	v_pk_mul_f32 v[10:11], v[26:27], v[10:11]
	v_mov_b32_e32 v43, v6
	v_mov_b32_e32 v6, v5
	v_pk_mul_f32 v[8:9], v[24:25], v[8:9]
	v_mov_b32_e32 v42, v4
	v_pk_mul_f32 v[4:5], v[6:7], v[10:11]
	s_nop 0
	v_pk_fma_f32 v[4:5], v[42:43], v[8:9], v[4:5] neg_lo:[0,0,1] neg_hi:[0,0,1]
	s_nop 0
	v_cvt_pk_bf16_f32 v14, v4, v5
	v_pk_mul_f32 v[4:5], v[42:43], v[10:11]
	s_nop 0
	v_pk_fma_f32 v[4:5], v[6:7], v[8:9], v[4:5]
	v_pk_mul_f32 v[6:7], v[50:51], v[38:39] op_sel_hi:[0,1]
	v_cvt_pk_bf16_f32 v48, v4, v5
	v_pk_mul_f32 v[4:5], v[50:51], v[40:41] op_sel_hi:[0,1]
	v_pk_mul_f32 v[6:7], v[30:31], v[6:7]
	v_mov_b32_e32 v9, v2
	v_mov_b32_e32 v2, v1
	v_pk_mul_f32 v[4:5], v[28:29], v[4:5]
	v_mov_b32_e32 v8, v0
	v_pk_mul_f32 v[0:1], v[2:3], v[6:7]
	s_nop 0
	v_pk_fma_f32 v[0:1], v[8:9], v[4:5], v[0:1] neg_lo:[0,0,1] neg_hi:[0,0,1]
	s_nop 0
	v_cvt_pk_bf16_f32 v15, v0, v1
	v_pk_mul_f32 v[0:1], v[8:9], v[6:7]
	s_nop 0
	v_pk_fma_f32 v[0:1], v[2:3], v[4:5], v[0:1]
	s_nop 0
	v_cvt_pk_bf16_f32 v49, v0, v1
	global_store_dwordx4 v[36:37], v[12:15], off
	global_store_dwordx4 v[36:37], v[46:49], off offset:64
	s_cmp_lg_u32 s15, 0
	s_cbranch_scc0 .Lpq_exit
	s_cmpk_lt_i32 s14, 0x4000
	s_cselect_b32 s15, 1, 0
	s_waitcnt vmcnt(10)
	v_mov_b32_e32 v46, v132
	v_mov_b32_e32 v47, v133
	v_mov_b32_e32 v48, v134
	v_mov_b32_e32 v49, v135
	v_mov_b32_e32 v50, v136
	v_mov_b32_e32 v51, v137
	v_mov_b32_e32 v52, v138
	v_mov_b32_e32 v53, v139
	v_mov_b32_e32 v12, v140
	v_mov_b32_e32 v13, v141
	v_mov_b32_e32 v14, v142
	v_mov_b32_e32 v15, v143
	v_mov_b32_e32 v0, v144
	v_mov_b32_e32 v1, v145
	v_mov_b32_e32 v2, v146
	v_mov_b32_e32 v3, v147
	v_mov_b32_e32 v4, v148
	v_mov_b32_e32 v5, v149
	v_mov_b32_e32 v6, v150
	v_mov_b32_e32 v7, v151
	v_mov_b32_e32 v8, v152
	v_mov_b32_e32 v9, v153
	v_mov_b32_e32 v10, v154
	v_mov_b32_e32 v11, v155
	v_mov_b32_e32 v36, v96
	v_mov_b32_e32 v37, v97
	v_lshl_add_u64 v[98:99], s[16:17], 0, v[34:35]
	v_add_co_u32_e32 v96, vcc, 0xc000000, v98
	s_mov_b64 s[6:7], 0xf600000
	s_nop 0
	v_addc_co_u32_e32 v97, vcc, 0, v99, vcc
	global_load_dwordx4 v[132:135], v[96:97], off
	global_load_dwordx4 v[136:139], v[96:97], off offset:64
	v_lshl_add_u64 v[98:99], s[16:17], 0, v[32:33]
	s_mov_b32 s1, 0xf600000
	v_lshl_add_u64 v[156:157], v[98:99], 0, s[6:7]
	v_add_co_u32_e32 v98, vcc, s1, v98
	s_add_i32 s14, s14, s38
	s_nop 0
	v_addc_co_u32_e32 v99, vcc, 0, v99, vcc
	global_load_dwordx4 v[140:143], v[98:99], off
	s_nop 0
	global_load_dwordx4 v[144:147], v[156:157], off offset:48
	global_load_dwordx4 v[148:151], v[156:157], off offset:32
	s_nop 0
	global_load_dwordx4 v[152:155], v[156:157], off offset:16
	v_lshl_add_u64 v[32:33], v[32:33], 0, s[66:67]
	v_lshl_add_u64 v[34:35], v[34:35], 0, s[62:63]
	v_lshlrev_b32_e32 v40, 16, v49
	v_lshlrev_b32_e32 v38, 16, v53
	v_and_b32_e32 v39, 0xffff0000, v53
	v_and_b32_e32 v41, 0xffff0000, v49
	v_pk_mul_f32 v[42:43], v[38:39], v[38:39]
	v_and_b32_e32 v53, 0xffff0000, v47
	v_pk_fma_f32 v[54:55], v[40:41], v[40:41], v[42:43]
	v_lshlrev_b32_e32 v42, 16, v52
	v_and_b32_e32 v43, 0xffff0000, v52
	v_lshlrev_b32_e32 v52, 16, v47
	v_lshlrev_b32_e32 v60, 16, v46
	v_and_b32_e32 v61, 0xffff0000, v46
	v_lshlrev_b32_e32 v46, 16, v50
	v_and_b32_e32 v47, 0xffff0000, v50
	v_lshlrev_b32_e32 v56, 16, v51
	v_and_b32_e32 v57, 0xffff0000, v51
	v_pk_mul_f32 v[50:51], v[46:47], v[46:47]
	v_pk_mul_f32 v[58:59], v[56:57], v[56:57]
	v_pk_fma_f32 v[50:51], v[60:61], v[60:61], v[50:51]
	v_pk_fma_f32 v[58:59], v[52:53], v[52:53], v[58:59]
	v_add_f32_e32 v50, v50, v51
	v_lshlrev_b32_e32 v44, 16, v48
	v_and_b32_e32 v45, 0xffff0000, v48
	v_pk_mul_f32 v[48:49], v[42:43], v[42:43]
	v_add_f32_e32 v50, v58, v50
	v_pk_fma_f32 v[48:49], v[44:45], v[44:45], v[48:49]
	v_add_f32_e32 v50, v59, v50
	v_add_f32_e32 v48, v48, v50
	v_add_f32_e32 v48, v49, v48
	v_add_f32_e32 v48, v54, v48
	v_add_f32_e32 v48, v55, v48
	s_nop 1
	v_add_f32_dpp v48, v48, v48 quad_perm:[1,0,3,2] row_mask:0xf bank_mask:0xf bound_ctrl:1
	s_nop 1
	v_add_f32_dpp v48, v48, v48 quad_perm:[2,3,0,1] row_mask:0xf bank_mask:0xf bound_ctrl:1
	v_fmamk_f32 v48, v48, 0x3c800000, v182
	v_cmp_gt_f32_e32 vcc, s50, v48
	v_mul_f32_e32 v49, 0x4f800000, v48
	s_nop 0
	v_cndmask_b32_e32 v48, v48, v49, vcc
	v_sqrt_f32_e32 v49, v48
	s_nop 0
	v_add_u32_e32 v50, -1, v49
	v_fma_f32 v51, -v50, v49, v48
	v_cmp_ge_f32_e64 s[12:13], 0, v51
	v_add_u32_e32 v51, 1, v49
	s_nop 0
	v_cndmask_b32_e64 v50, v49, v50, s[12:13]
	v_fma_f32 v49, -v51, v49, v48
	v_cmp_lt_f32_e64 s[12:13], 0, v49
	s_nop 1
	v_cndmask_b32_e64 v49, v50, v51, s[12:13]
	v_mul_f32_e32 v50, 0x37800000, v49
	v_cndmask_b32_e32 v49, v49, v50, vcc
	v_cmp_class_f32_e32 vcc, v48, v183
	s_nop 1
	v_cndmask_b32_e32 v48, v49, v48, vcc
	v_div_scale_f32 v49, s[6:7], v48, v48, 1.0
	v_rcp_f32_e32 v50, v49
	s_nop 0
	v_fma_f32 v51, -v49, v50, 1.0
	v_fmac_f32_e32 v50, v51, v50
	v_div_scale_f32 v51, vcc, 1.0, v48, 1.0
	v_mul_f32_e32 v54, v51, v50
	v_fma_f32 v55, -v49, v54, v51
	v_fmac_f32_e32 v54, v55, v50
	v_fma_f32 v49, -v49, v54, v51
	v_div_fmas_f32 v49, v49, v50, v54
	v_div_fixup_f32 v50, v49, v48, 1.0
	v_pk_mul_f32 v[46:47], v[50:51], v[46:47] op_sel_hi:[0,1]
	v_pk_mul_f32 v[48:49], v[50:51], v[60:61] op_sel_hi:[0,1]
	v_pk_mul_f32 v[46:47], v[18:19], v[46:47]
	v_mov_b32_e32 v54, v12
	v_mov_b32_e32 v55, v14
	v_mov_b32_e32 v14, v13
	v_pk_mul_f32 v[48:49], v[16:17], v[48:49]
	v_pk_mul_f32 v[12:13], v[14:15], v[46:47]
	v_pk_mul_f32 v[46:47], v[54:55], v[46:47]
	v_pk_fma_f32 v[12:13], v[54:55], v[48:49], v[12:13] neg_lo:[0,0,1] neg_hi:[0,0,1]
	v_pk_fma_f32 v[14:15], v[14:15], v[48:49], v[46:47]
	v_pk_mul_f32 v[48:49], v[50:51], v[56:57] op_sel_hi:[0,1]
	v_cvt_pk_bf16_f32 v46, v14, v15
	v_pk_mul_f32 v[14:15], v[50:51], v[52:53] op_sel_hi:[0,1]
	v_pk_mul_f32 v[48:49], v[22:23], v[48:49]
	v_mov_b32_e32 v53, v10
	v_mov_b32_e32 v10, v9
	v_pk_mul_f32 v[14:15], v[20:21], v[14:15]
	v_mov_b32_e32 v52, v8
	v_pk_mul_f32 v[8:9], v[10:11], v[48:49]
	v_cvt_pk_bf16_f32 v12, v12, v13
	v_pk_fma_f32 v[8:9], v[52:53], v[14:15], v[8:9] neg_lo:[0,0,1] neg_hi:[0,0,1]
	s_nop 0
	v_cvt_pk_bf16_f32 v13, v8, v9
	v_pk_mul_f32 v[8:9], v[52:53], v[48:49]
	s_nop 0
	v_pk_fma_f32 v[8:9], v[10:11], v[14:15], v[8:9]
	v_pk_mul_f32 v[10:11], v[50:51], v[42:43] op_sel_hi:[0,1]
	v_cvt_pk_bf16_f32 v47, v8, v9
	v_pk_mul_f32 v[8:9], v[50:51], v[44:45] op_sel_hi:[0,1]
	v_pk_mul_f32 v[10:11], v[26:27], v[10:11]
	v_mov_b32_e32 v43, v6
	v_mov_b32_e32 v6, v5
	v_pk_mul_f32 v[8:9], v[24:25], v[8:9]
	v_mov_b32_e32 v42, v4
	v_pk_mul_f32 v[4:5], v[6:7], v[10:11]
	s_nop 0
	v_pk_fma_f32 v[4:5], v[42:43], v[8:9], v[4:5] neg_lo:[0,0,1] neg_hi:[0,0,1]
	s_nop 0
	v_cvt_pk_bf16_f32 v14, v4, v5
	v_pk_mul_f32 v[4:5], v[42:43], v[10:11]
	s_nop 0
	v_pk_fma_f32 v[4:5], v[6:7], v[8:9], v[4:5]
	v_pk_mul_f32 v[6:7], v[50:51], v[38:39] op_sel_hi:[0,1]
	v_cvt_pk_bf16_f32 v48, v4, v5
	v_pk_mul_f32 v[4:5], v[50:51], v[40:41] op_sel_hi:[0,1]
	v_pk_mul_f32 v[6:7], v[30:31], v[6:7]
	v_mov_b32_e32 v9, v2
	v_mov_b32_e32 v2, v1
	v_pk_mul_f32 v[4:5], v[28:29], v[4:5]
	v_mov_b32_e32 v8, v0
	v_pk_mul_f32 v[0:1], v[2:3], v[6:7]
	s_nop 0
	v_pk_fma_f32 v[0:1], v[8:9], v[4:5], v[0:1] neg_lo:[0,0,1] neg_hi:[0,0,1]
	s_nop 0
	v_cvt_pk_bf16_f32 v15, v0, v1
	v_pk_mul_f32 v[0:1], v[8:9], v[6:7]
	s_nop 0
	v_pk_fma_f32 v[0:1], v[2:3], v[4:5], v[0:1]
	s_nop 0
	v_cvt_pk_bf16_f32 v49, v0, v1
	global_store_dwordx4 v[36:37], v[12:15], off
	global_store_dwordx4 v[36:37], v[46:49], off offset:64
	s_cmp_lg_u32 s42, 0
	s_cbranch_scc1 .LBB0_341
.Lpq_exit:
	s_waitcnt vmcnt(0)
.LBB0_342:
	s_mov_b64 s[12:13], s[84:85]
	v_mov_b32_e32 v0, v173
	s_getreg_b32 s1, hwreg(HW_REG_HW_ID, 0, 7)
	s_and_b32 s1, s1, 63
	s_lshl_b32 s1, s1, 2
	v_mov_b32_e32 v1, s1
	ds_read_b32 v1, v1
	s_and_b64 vcc, exec, s[10:11]
	s_waitcnt lgkmcnt(0)
	v_readfirstlane_b32 s7, v1
	s_cbranch_vccnz .LBB0_346
	v_readlane_b32 s8, v254, 53
	v_readlane_b32 s9, v254, 54
	s_andn2_b64 vcc, exec, s[8:9]
	s_cbranch_vccnz .LBB0_346
	s_load_dwordx2 s[8:9], s[12:13], 0xe0
	v_and_b32_e32 v1, 15, v0
	v_lshlrev_b32_e32 v6, 3, v0
	v_and_b32_e32 v14, 56, v6
	v_lshlrev_b32_e32 v12, 3, v1
	s_waitcnt lgkmcnt(0)
	s_add_u32 s10, s8, 0xc000000
	s_addc_u32 s11, s9, 0
	s_add_u32 s1, s8, 0x3000000
	s_addc_u32 s6, s9, 0
	s_lshl_b32 s7, s7, 6
	s_and_b32 s7, s7, 0x3fc0
	v_add_u32_e32 v4, s7, v0
	v_ashrrev_i32_e32 v2, 4, v4
	s_movk_i32 s7, 0x104
	v_mul_lo_u32 v3, v2, s7
	v_add_u32_e32 v9, 0x200, v4
	v_lshlrev_b32_e32 v0, 2, v0
	v_add_u32_e32 v11, 0x120, v3
	v_ashrrev_i32_e32 v3, 4, v9
	v_and_b32_e32 v0, 4, v0
	v_mul_lo_u32 v5, v3, s7
	v_and_or_b32 v6, v6, 48, v0
	v_or_b32_e32 v0, v0, v14
	v_lshlrev_b32_e32 v1, 4, v1
	v_add_u32_e32 v13, 0x120, v5
	v_ashrrev_i32_e32 v4, 3, v4
	v_or_b32_e32 v7, 8, v0
	v_or_b32_e32 v0, 10, v0
	v_ashrrev_i32_e32 v9, 3, v9
	v_lshl_add_u32 v5, v4, 1, v195
	v_mul_u32_u24_e32 v6, 0x104, v6
	v_mul_u32_u24_e32 v7, 0x104, v7
	v_mul_u32_u24_e32 v8, 0x104, v0
	v_lshl_add_u32 v10, v9, 1, v195
	v_lshlrev_b32_e32 v160, 1, v12
	v_add_u32_e32 v11, v11, v1
	v_add_u32_e32 v12, v13, v1
	v_lshlrev_b32_e32 v0, 1, v14
	v_readlane_b32 s7, v254, 47
	v_readlane_b32 s8, v254, 46
	v_mov_b32_e32 v13, v193
	s_and_b32 s16, s7, 0xffffffc0
	s_and_b32 s18, s8, 0x180
	s_lshl_b32 s18, s18, 1
	s_mov_b32 s19, 0
	v_mov_b64_e32 v[110:111], s[10:11]
	v_add_u32_e32 v112, s16, v2
	v_mad_i64_i32 v[108:109], s[14:15], v112, s78, v[110:111]
	v_lshl_add_u64 v[108:109], v[108:109], 0, s[18:19]
	v_lshl_add_u64 v[108:109], v[108:109], 0, v[160:161]
	global_load_dwordx4 v[100:103], v[108:109], off offset:2048
	v_add_u32_e32 v112, s16, v3
	v_mad_i64_i32 v[108:109], s[14:15], v112, s78, v[110:111]
	v_lshl_add_u64 v[108:109], v[108:109], 0, s[18:19]
	v_lshl_add_u64 v[108:109], v[108:109], 0, v[160:161]
	global_load_dwordx4 v[104:107], v[108:109], off offset:2048
	s_mov_b32 s17, 1
